# v18
# speedup vs baseline: 1.0106x; 1.0001x over previous
.LBB0_198:
	v_mov_b32_e32 v96, v167
	s_lshl_b32 s5, s5, 3
	v_lshlrev_b32_e32 v0, 2, v96
	v_and_b32_e32 v94, 4, v0
	v_or_b32_e32 v88, s5, v94
	v_mov_b32_e32 v89, v1
	v_readlane_b32 s60, v251, 45
	s_waitcnt vmcnt(0)
	v_lshlrev_b64 v[50:51], 2, v[88:89]
	v_readlane_b32 s64, v251, 49
	v_readlane_b32 s65, v251, 50
	s_movk_i32 s9, 0x7000
	v_readlane_b32 s66, v251, 51
	v_lshl_add_u64 v[42:43], s[64:65], 0, v[50:51]
	v_add_co_u32_e32 v44, vcc, s59, v42
	v_readlane_b32 s67, v251, 52
	s_nop 0
	v_addc_co_u32_e32 v45, vcc, 0, v43, vcc
	v_add_co_u32_e32 v14, vcc, s9, v42
	v_lshl_add_u64 v[6:7], s[66:67], 0, v[50:51]
	s_nop 0
	v_addc_co_u32_e32 v15, vcc, 0, v43, vcc
	v_add_co_u32_e32 v22, vcc, s3, v6
	global_load_dwordx4 v[2:5], v[6:7], off
	s_nop 0
	v_addc_co_u32_e32 v23, vcc, 0, v7, vcc
	v_add_co_u32_e32 v30, vcc, s3, v42
	s_movk_i32 s9, 0x5000
	s_nop 0
	v_addc_co_u32_e32 v31, vcc, 0, v43, vcc
	global_load_dwordx4 v[6:9], v[14:15], off offset:-4096
	global_load_dwordx4 v[10:13], v[44:45], off
	s_nop 0
	global_load_dwordx4 v[14:17], v[14:15], off
	s_nop 0
	global_load_dwordx4 v[18:21], v[22:23], off offset:-4096
	s_nop 0
	global_load_dwordx4 v[22:25], v[22:23], off
	s_nop 0
	global_load_dwordx4 v[26:29], v[30:31], off offset:-4096
	s_nop 0
	global_load_dwordx4 v[30:33], v[30:31], off
	v_add_co_u32_e32 v38, vcc, s9, v42
	s_mov_b32 s9, 0x8000
	s_nop 0
	v_addc_co_u32_e32 v39, vcc, 0, v43, vcc
	v_add_co_u32_e32 v46, vcc, s9, v42
	global_load_dwordx4 v[34:37], v[42:43], off
	s_nop 0
	global_load_dwordx4 v[38:41], v[38:39], off
	v_addc_co_u32_e32 v47, vcc, 0, v43, vcc
	global_load_dwordx4 v[42:45], v[44:45], off offset:-4096
	s_nop 0
	global_load_dwordx4 v[46:49], v[46:47], off
	v_ashrrev_i32_e32 v86, 1, v96
	s_movk_i32 s22, 0x3000
	v_mad_i64_i32 v[52:53], s[22:23], v86, s22, 0
	v_mov_b32_e32 v0, 0x3000
	v_mad_u64_u32 v[52:53], s[22:23], s44, v0, v[52:53]
	s_mul_i32 s22, s45, 0x3000
	s_movk_i32 s24, 0x4200
	v_add_u32_e32 v53, s22, v53
	v_and_b32_e32 v0, -2, v96
	v_lshl_add_u64 v[50:51], v[52:53], 0, v[50:51]
	v_mad_u32_u24 v0, v94, s24, v0
	s_lshr_b32 s9, s6, 1
	v_mad_u32_u24 v95, v94, s24, 0
	s_add_i32 s17, s6, -1
	v_ashrrev_i32_e32 v87, 31, v86
	v_lshl_add_u64 v[90:91], s[20:21], 0, v[50:51]
	s_movk_i32 s26, 0x4200
	v_add_u32_e32 v97, 0, v0
	s_mov_b64 s[24:25], 0
	v_mov_b32_e32 v98, v86
	v_readlane_b32 s61, v251, 46
	v_readlane_b32 s62, v251, 47
	v_readlane_b32 s63, v251, 48
	v_readlane_b32 s68, v251, 53
	v_readlane_b32 s69, v251, 54
	v_readlane_b32 s70, v251, 55
	v_readlane_b32 s71, v251, 56
	v_readlane_b32 s72, v251, 57
	v_readlane_b32 s73, v251, 58
	v_readlane_b32 s74, v251, 59
	v_readlane_b32 s75, v251, 60
	v_mbcnt_lo_u32_b32 v125, -1, 0
	v_mbcnt_hi_u32_b32 v125, -1, v125
	v_add_u32_e32 v126, 2, v125
	v_add_u32_e32 v125, -2, v125
	v_and_b32_e32 v125, 63, v125
	v_and_b32_e32 v126, 63, v126
	v_lshlrev_b32_e32 v125, 2, v125
	v_lshlrev_b32_e32 v126, 2, v126
	s_branch .LBB0_200
.LBB0_199:
	s_or_b64 exec, exec, s[40:41]
	s_waitcnt vmcnt(0)
	ds_bpermute_b32 v101, v125, v58
	ds_bpermute_b32 v102, v125, v59
	ds_bpermute_b32 v103, v125, v60
	ds_bpermute_b32 v104, v125, v61
	ds_bpermute_b32 v105, v125, v78
	ds_bpermute_b32 v106, v125, v79
	ds_bpermute_b32 v107, v125, v80
	ds_bpermute_b32 v108, v125, v81
	ds_bpermute_b32 v109, v125, v82
	ds_bpermute_b32 v110, v125, v83
	ds_bpermute_b32 v111, v125, v84
	ds_bpermute_b32 v112, v125, v85
	s_mov_b64 vcc, 3
	s_waitcnt lgkmcnt(0)
	v_cndmask_b32_e32 v54, v101, v54, vcc
	v_cndmask_b32_e32 v55, v102, v55, vcc
	v_cndmask_b32_e32 v56, v103, v56, vcc
	v_cndmask_b32_e32 v57, v104, v57, vcc
	v_cndmask_b32_e32 v66, v105, v66, vcc
	v_cndmask_b32_e32 v67, v106, v67, vcc
	v_cndmask_b32_e32 v68, v107, v68, vcc
	v_cndmask_b32_e32 v69, v108, v69, vcc
	v_cndmask_b32_e32 v74, v109, v74, vcc
	v_cndmask_b32_e32 v75, v110, v75, vcc
	v_cndmask_b32_e32 v76, v111, v76, vcc
	v_cndmask_b32_e32 v77, v112, v77, vcc
	ds_bpermute_b32 v101, v126, v58
	ds_bpermute_b32 v102, v126, v59
	ds_bpermute_b32 v103, v126, v60
	ds_bpermute_b32 v104, v126, v61
	ds_bpermute_b32 v105, v126, v78
	ds_bpermute_b32 v106, v126, v79
	ds_bpermute_b32 v107, v126, v80
	ds_bpermute_b32 v108, v126, v81
	ds_bpermute_b32 v109, v126, v82
	ds_bpermute_b32 v110, v126, v83
	ds_bpermute_b32 v111, v126, v84
	ds_bpermute_b32 v112, v126, v85
	s_mov_b32 vcc_lo, 0
	s_mov_b32 vcc_hi, 0xc0000000
	s_waitcnt lgkmcnt(0)
	v_cndmask_b32_e32 v50, v101, v50, vcc
	v_cndmask_b32_e32 v51, v102, v51, vcc
	v_cndmask_b32_e32 v52, v103, v52, vcc
	v_cndmask_b32_e32 v53, v104, v53, vcc
	v_cndmask_b32_e32 v62, v105, v62, vcc
	v_cndmask_b32_e32 v63, v106, v63, vcc
	v_cndmask_b32_e32 v64, v107, v64, vcc
	v_cndmask_b32_e32 v65, v108, v65, vcc
	v_cndmask_b32_e32 v70, v109, v70, vcc
	v_cndmask_b32_e32 v71, v110, v71, vcc
	v_cndmask_b32_e32 v72, v111, v72, vcc
	v_cndmask_b32_e32 v73, v112, v73, vcc
	s_waitcnt vmcnt(2)
	v_pk_mul_f32 v[58:59], v[42:43], v[58:59]
	v_pk_mul_f32 v[60:61], v[44:45], v[60:61]
	v_pk_fma_f32 v[54:55], v[34:35], v[54:55], v[58:59]
	v_ashrrev_i32_e32 v58, s14, v100
	v_mul_lo_u32 v58, v58, s6
	s_waitcnt vmcnt(1)
	v_pk_mul_f32 v[78:79], v[10:11], v[78:79]
	v_pk_fma_f32 v[56:57], v[36:37], v[56:57], v[60:61]
	v_pk_fma_f32 v[50:51], v[6:7], v[50:51], v[54:55]
	v_lshlrev_b32_e32 v58, 2, v58
	v_lshlrev_b32_e32 v60, 1, v99
	v_pk_fma_f32 v[66:67], v[26:27], v[66:67], v[78:79]
	v_pk_fma_f32 v[52:53], v[8:9], v[52:53], v[56:57]
	v_pk_add_f32 v[50:51], v[2:3], v[50:51]
	s_waitcnt vmcnt(0)
	v_pk_mul_f32 v[56:57], v[38:39], v[82:83]
	v_add3_u32 v58, v95, v58, v60
	v_pk_fma_f32 v[62:63], v[14:15], v[62:63], v[66:67]
	v_pk_fma_f32 v[56:57], v[30:31], v[74:75], v[56:57]
	v_cvt_pk_bf16_f32 v50, v50, v1
	v_add_u32_e32 v60, s6, v58
	v_pk_add_f32 v[62:63], v[18:19], v[62:63]
	v_pk_fma_f32 v[56:57], v[46:47], v[70:71], v[56:57]
	v_mov_b32_e32 v59, s6
	v_cmp_le_i32_e32 vcc, s9, v99
	ds_write_b16 v60, v50
	v_cvt_pk_bf16_f32 v50, v62, v1
	v_pk_add_f32 v[56:57], v[22:23], v[56:57]
	v_cndmask_b32_e32 v59, 0, v59, vcc
	ds_write_b16 v97, v50 offset:13312
	v_cvt_pk_bf16_f32 v50, v56, v1
	ds_write_b16 v97, v50 offset:15360
	v_lshl_add_u32 v50, v59, 1, v58
	v_cvt_pk_bf16_f32 v51, v51, v1
	v_pk_mul_f32 v[80:81], v[12:13], v[80:81]
	ds_write_b16 v50, v1
	ds_write_b16 v50, v1 offset:4096
	ds_write_b16 v60, v51 offset:16896
	v_cvt_pk_bf16_f32 v51, v63, v1
	v_pk_fma_f32 v[68:69], v[28:29], v[68:69], v[80:81]
	v_pk_mul_f32 v[54:55], v[40:41], v[84:85]
	ds_write_b16 v97, v51 offset:30208
	v_cvt_pk_bf16_f32 v51, v57, v1
	v_pk_fma_f32 v[64:65], v[16:17], v[64:65], v[68:69]
	v_pk_add_f32 v[52:53], v[4:5], v[52:53]
	v_pk_fma_f32 v[54:55], v[32:33], v[76:77], v[54:55]
	ds_write_b16 v97, v51 offset:32256
	ds_write_b16 v50, v1 offset:16896
	ds_write_b16 v50, v1 offset:20992
	v_cvt_pk_bf16_f32 v51, v52, v1
	v_pk_add_f32 v[64:65], v[20:21], v[64:65]
	v_pk_fma_f32 v[54:55], v[48:49], v[72:73], v[54:55]
	ds_write_b16 v60, v51 offset:33792
	v_cvt_pk_bf16_f32 v51, v64, v1
	v_pk_add_f32 v[54:55], v[24:25], v[54:55]
	ds_write_b16 v97, v51 offset:47104
	v_cvt_pk_bf16_f32 v51, v54, v1
	ds_write_b16 v97, v51 offset:49152
	ds_write_b16 v50, v1 offset:33792
	ds_write_b16 v50, v1 offset:37888
	v_cvt_pk_bf16_f32 v51, v53, v1
	s_add_u32 s24, s24, 0x600000
	ds_write_b16 v60, v51 offset:50688
	v_cvt_pk_bf16_f32 v51, v65, v1
	s_addc_u32 s25, s25, 0
	ds_write_b16 v97, v51 offset:64000
	v_cvt_pk_bf16_f32 v51, v55, v1
	v_add_u32_e32 v52, 0x10200, v97
	v_add_u32_e32 v98, 0x200, v98
	s_cmp_eq_u32 s24, 0xc00000
	v_add_u32_e32 v97, 0x400, v97
	ds_write_b16 v52, v51
	ds_write_b16 v50, v1 offset:50688
	ds_write_b16 v50, v1 offset:54784
	s_cbranch_scc1 .LBB0_224
.LBB0_200:
	v_and_b32_e32 v99, s17, v98
	v_lshl_add_u64 v[92:93], v[90:91], 0, s[24:25]
	v_cmp_lt_i32_e64 s[40:41], 0, v99
	s_nop 1
	s_and_b64 s[40:41], s[40:41], 3
	v_mov_b32_e32 v50, 0
	v_mov_b32_e32 v54, 0
	v_mov_b32_e32 v55, 0
	v_mov_b32_e32 v56, 0
	v_mov_b32_e32 v57, 0
	s_and_saveexec_b64 s[42:43], s[40:41]
	s_cbranch_execz .LBB0_202
	v_add_co_u32_e32 v52, vcc, 0x261fd000, v92
	s_nop 1
	v_addc_co_u32_e32 v53, vcc, 0, v93, vcc
	global_load_dwordx4 v[54:57], v[52:53], off
.LBB0_202:
	s_or_b64 exec, exec, s[42:43]
	v_add_co_u32_e32 v52, vcc, 0x26200000, v92
	v_cmp_gt_i32_e64 s[42:43], s17, v99
	s_nop 1
	s_mov_b32 s42, 0
	s_and_b32 s43, s43, 0xc0000000
	s_nop 0
	v_addc_co_u32_e32 v53, vcc, 0, v93, vcc
	global_load_dwordx4 v[58:61], v[52:53], off
	v_mov_b32_e32 v51, 0
	v_mov_b32_e32 v52, 0
	v_mov_b32_e32 v53, 0
	s_and_saveexec_b64 s[46:47], s[42:43]
	s_cbranch_execz .LBB0_204
	v_add_co_u32_e32 v50, vcc, 0x26203000, v92
	s_nop 1
	v_addc_co_u32_e32 v51, vcc, 0, v93, vcc
	global_load_dwordx4 v[50:53], v[50:51], off

.LBB0_212:
	s_or_b64 exec, exec, s[40:41]
	s_waitcnt vmcnt(0)
	ds_bpermute_b32 v101, v125, v58
	ds_bpermute_b32 v102, v125, v59
	ds_bpermute_b32 v103, v125, v60
	ds_bpermute_b32 v104, v125, v61
	ds_bpermute_b32 v105, v125, v78
	ds_bpermute_b32 v106, v125, v79
	ds_bpermute_b32 v107, v125, v80
	ds_bpermute_b32 v108, v125, v81
	ds_bpermute_b32 v109, v125, v82
	ds_bpermute_b32 v110, v125, v83
	ds_bpermute_b32 v111, v125, v84
	ds_bpermute_b32 v112, v125, v85
	s_mov_b64 vcc, 3
	s_waitcnt lgkmcnt(0)
	v_cndmask_b32_e32 v54, v101, v54, vcc
	v_cndmask_b32_e32 v55, v102, v55, vcc
	v_cndmask_b32_e32 v56, v103, v56, vcc
	v_cndmask_b32_e32 v57, v104, v57, vcc
	v_cndmask_b32_e32 v66, v105, v66, vcc
	v_cndmask_b32_e32 v67, v106, v67, vcc
	v_cndmask_b32_e32 v68, v107, v68, vcc
	v_cndmask_b32_e32 v69, v108, v69, vcc
	v_cndmask_b32_e32 v74, v109, v74, vcc
	v_cndmask_b32_e32 v75, v110, v75, vcc
	v_cndmask_b32_e32 v76, v111, v76, vcc
	v_cndmask_b32_e32 v77, v112, v77, vcc
	ds_bpermute_b32 v101, v126, v58
	ds_bpermute_b32 v102, v126, v59
	ds_bpermute_b32 v103, v126, v60
	ds_bpermute_b32 v104, v126, v61
	ds_bpermute_b32 v105, v126, v78
	ds_bpermute_b32 v106, v126, v79
	ds_bpermute_b32 v107, v126, v80
	ds_bpermute_b32 v108, v126, v81
	ds_bpermute_b32 v109, v126, v82
	ds_bpermute_b32 v110, v126, v83
	ds_bpermute_b32 v111, v126, v84
	ds_bpermute_b32 v112, v126, v85
	s_mov_b32 vcc_lo, 0
	s_mov_b32 vcc_hi, 0xc0000000
	s_waitcnt lgkmcnt(0)
	v_cndmask_b32_e32 v50, v101, v50, vcc
	v_cndmask_b32_e32 v51, v102, v51, vcc
	v_cndmask_b32_e32 v52, v103, v52, vcc
	v_cndmask_b32_e32 v53, v104, v53, vcc
	v_cndmask_b32_e32 v62, v105, v62, vcc
	v_cndmask_b32_e32 v63, v106, v63, vcc
	v_cndmask_b32_e32 v64, v107, v64, vcc
	v_cndmask_b32_e32 v65, v108, v65, vcc
	v_cndmask_b32_e32 v70, v109, v70, vcc
	v_cndmask_b32_e32 v71, v110, v71, vcc
	v_cndmask_b32_e32 v72, v111, v72, vcc
	v_cndmask_b32_e32 v73, v112, v73, vcc
	s_waitcnt vmcnt(2)
	v_pk_mul_f32 v[58:59], v[42:43], v[58:59]
	v_pk_mul_f32 v[60:61], v[44:45], v[60:61]
	v_pk_fma_f32 v[54:55], v[34:35], v[54:55], v[58:59]
	v_ashrrev_i32_e32 v58, s14, v98
	v_mul_lo_u32 v58, v58, s6
	s_waitcnt vmcnt(1)
	v_pk_mul_f32 v[78:79], v[10:11], v[78:79]
	v_pk_fma_f32 v[56:57], v[36:37], v[56:57], v[60:61]
	v_pk_fma_f32 v[50:51], v[6:7], v[50:51], v[54:55]
	v_lshlrev_b32_e32 v58, 2, v58
	v_lshlrev_b32_e32 v60, 1, v99
	v_pk_fma_f32 v[66:67], v[26:27], v[66:67], v[78:79]
	v_pk_fma_f32 v[52:53], v[8:9], v[52:53], v[56:57]
	v_pk_add_f32 v[50:51], v[2:3], v[50:51]
	s_waitcnt vmcnt(0)
	v_pk_mul_f32 v[56:57], v[38:39], v[82:83]
	v_add3_u32 v58, v95, v58, v60
	v_pk_fma_f32 v[62:63], v[14:15], v[62:63], v[66:67]
	v_pk_fma_f32 v[56:57], v[30:31], v[74:75], v[56:57]
	v_cvt_pk_bf16_f32 v50, v50, v1
	v_add_u32_e32 v60, s6, v58
	v_pk_add_f32 v[62:63], v[18:19], v[62:63]
	v_pk_fma_f32 v[56:57], v[46:47], v[70:71], v[56:57]
	v_mov_b32_e32 v59, s6
	v_cmp_le_i32_e32 vcc, s9, v99
	ds_write_b16 v60, v50
	v_cvt_pk_bf16_f32 v50, v62, v1
	v_pk_add_f32 v[56:57], v[22:23], v[56:57]
	v_cndmask_b32_e32 v59, 0, v59, vcc
	ds_write_b16 v97, v50 offset:12800
	v_cvt_pk_bf16_f32 v50, v56, v1
	ds_write_b16 v97, v50 offset:14848
	v_lshl_add_u32 v50, v59, 1, v58
	v_cvt_pk_bf16_f32 v51, v51, v1
	v_pk_mul_f32 v[80:81], v[12:13], v[80:81]
	ds_write_b16 v50, v1
	ds_write_b16 v50, v1 offset:4096
	ds_write_b16 v60, v51 offset:16896
	v_cvt_pk_bf16_f32 v51, v63, v1
	v_pk_fma_f32 v[68:69], v[28:29], v[68:69], v[80:81]
	v_pk_mul_f32 v[54:55], v[40:41], v[84:85]
	ds_write_b16 v97, v51 offset:29696
	v_cvt_pk_bf16_f32 v51, v57, v1
	v_pk_fma_f32 v[64:65], v[16:17], v[64:65], v[68:69]
	v_pk_add_f32 v[52:53], v[4:5], v[52:53]
	v_pk_fma_f32 v[54:55], v[32:33], v[76:77], v[54:55]
	ds_write_b16 v97, v51 offset:31744
	ds_write_b16 v50, v1 offset:16896
	ds_write_b16 v50, v1 offset:20992
	v_cvt_pk_bf16_f32 v51, v52, v1
	v_pk_add_f32 v[64:65], v[20:21], v[64:65]
	v_pk_fma_f32 v[54:55], v[48:49], v[72:73], v[54:55]
	ds_write_b16 v60, v51 offset:33792
	v_cvt_pk_bf16_f32 v51, v64, v1
	v_pk_add_f32 v[54:55], v[24:25], v[54:55]
	ds_write_b16 v97, v51 offset:46592
	v_cvt_pk_bf16_f32 v51, v54, v1
	ds_write_b16 v97, v51 offset:48640
	ds_write_b16 v50, v1 offset:33792
	ds_write_b16 v50, v1 offset:37888
	v_cvt_pk_bf16_f32 v51, v53, v1
	ds_write_b16 v60, v51 offset:50688
	v_cvt_pk_bf16_f32 v51, v65, v1
	v_add_u32_e32 v100, 0x100, v98
	ds_write_b16 v97, v51 offset:63488
	v_cvt_pk_bf16_f32 v51, v55, v1
	v_add_u32_e32 v52, 0x10000, v97
	v_and_b32_e32 v99, s17, v100
	ds_write_b16 v52, v51
	ds_write_b16 v50, v1 offset:50688
	ds_write_b16 v50, v1 offset:54784
	v_cmp_lt_i32_e64 s[40:41], 0, v99
	s_nop 1
	s_and_b64 s[40:41], s[40:41], 3
	v_mov_b32_e32 v50, 0
	v_mov_b32_e32 v54, 0
	v_mov_b32_e32 v55, 0
	v_mov_b32_e32 v56, 0
	v_mov_b32_e32 v57, 0
	s_and_saveexec_b64 s[42:43], s[40:41]
	s_cbranch_execz .LBB0_214
	v_add_co_u32_e32 v52, vcc, 0x264fd000, v92
	s_nop 1
	v_addc_co_u32_e32 v53, vcc, 0, v93, vcc
	global_load_dwordx4 v[54:57], v[52:53], off
.LBB0_214:
	s_or_b64 exec, exec, s[42:43]
	v_add_co_u32_e32 v52, vcc, 0x26500000, v92
	v_cmp_gt_i32_e64 s[42:43], s17, v99
	s_nop 1
	s_mov_b32 s42, 0
	s_and_b32 s43, s43, 0xc0000000
	s_nop 0
	v_addc_co_u32_e32 v53, vcc, 0, v93, vcc
	global_load_dwordx4 v[58:61], v[52:53], off
	v_mov_b32_e32 v51, 0
	v_mov_b32_e32 v52, 0
	v_mov_b32_e32 v53, 0
	s_and_saveexec_b64 s[46:47], s[42:43]
	s_cbranch_execz .LBB0_216
	v_add_co_u32_e32 v50, vcc, 0x26503000, v92
	s_nop 1
	v_addc_co_u32_e32 v51, vcc, 0, v93, vcc
	global_load_dwordx4 v[50:53], v[50:51], off

.LBB0_254:
	v_readlane_b32 s80, v254, 35
	s_mov_b64 s[60:61], -1
	s_cmp_lt_i32 s53, 16
	v_lshl_add_u32 v140, s52, 8, v135
	v_readlane_b32 s81, v254, 36
	v_readlane_b32 s82, v254, 37
	v_readlane_b32 s83, v254, 38
	v_readlane_b32 s84, v254, 39
	v_readlane_b32 s85, v254, 40
	v_readlane_b32 s86, v254, 41
	v_readlane_b32 s87, v254, 42
	v_readlane_b32 s88, v254, 43
	v_readlane_b32 s89, v254, 44
	v_readlane_b32 s90, v254, 45
	v_readlane_b32 s91, v254, 46
	v_readlane_b32 s92, v254, 47
	v_readlane_b32 s93, v254, 48
	v_readlane_b32 s94, v254, 49
	v_readlane_b32 s95, v254, 50
	s_cbranch_scc1 .LBB0_257
	s_lshl_b32 s26, s53, 8
	v_mov_b64_e32 v[146:147], s[40:41]
	s_movk_i32 s45, 0x3000
	s_addk_i32 s26, 0xf000
	v_mad_i64_i32 v[148:149], s[60:61], v140, s45, v[146:147]
	s_lshl_b64 s[60:61], s[26:27], 2
	s_nop 0
	v_lshl_add_u64 v[148:149], v[148:149], 0, s[60:61]
	s_lshl_b32 s26, s68, 2
	v_lshl_add_u64 v[148:149], v[148:149], 0, s[26:27]
	v_lshlrev_b32_e32 v0, 2, v134
	v_lshl_add_u64 v[148:149], v[148:149], 0, v[0:1]
	v_or_b32_e32 v141, 16, v140
	global_store_dwordx4 v[148:149], v[126:129], off
	global_store_dwordx4 v[148:149], v[122:125], off offset:64
	global_store_dwordx4 v[148:149], v[118:121], off offset:512
	global_store_dwordx4 v[148:149], v[110:113], off offset:576
	v_mad_i64_i32 v[148:149], s[62:63], v141, s45, v[146:147]
	v_lshl_add_u64 v[148:149], v[148:149], 0, s[60:61]
	v_lshl_add_u64 v[148:149], v[148:149], 0, s[26:27]
	v_lshl_add_u64 v[148:149], v[148:149], 0, v[0:1]
	v_or_b32_e32 v141, 32, v140
	global_store_dwordx4 v[148:149], v[114:117], off
	global_store_dwordx4 v[148:149], v[106:109], off offset:64
	global_store_dwordx4 v[148:149], v[102:105], off offset:512
	global_store_dwordx4 v[148:149], v[94:97], off offset:576
	v_mad_i64_i32 v[148:149], s[62:63], v141, s45, v[146:147]
	v_lshl_add_u64 v[148:149], v[148:149], 0, s[60:61]
	v_lshl_add_u64 v[148:149], v[148:149], 0, s[26:27]
	v_lshl_add_u64 v[148:149], v[148:149], 0, v[0:1]
	v_or_b32_e32 v141, 48, v140
	global_store_dwordx4 v[148:149], v[98:101], off
	global_store_dwordx4 v[148:149], v[90:93], off offset:64
	global_store_dwordx4 v[148:149], v[86:89], off offset:512
	global_store_dwordx4 v[148:149], v[78:81], off offset:576
	v_mad_i64_i32 v[148:149], s[62:63], v141, s45, v[146:147]
	v_lshl_add_u64 v[148:149], v[148:149], 0, s[60:61]
	v_lshl_add_u64 v[148:149], v[148:149], 0, s[26:27]
	v_lshl_add_u64 v[148:149], v[148:149], 0, v[0:1]
	v_add_u32_e32 v141, 0x80, v140
	global_store_dwordx4 v[148:149], v[82:85], off
	global_store_dwordx4 v[148:149], v[74:77], off offset:64
	global_store_dwordx4 v[148:149], v[70:73], off offset:512
	global_store_dwordx4 v[148:149], v[66:69], off offset:576
	v_mad_i64_i32 v[148:149], s[62:63], v141, s45, v[146:147]
	v_lshl_add_u64 v[148:149], v[148:149], 0, s[60:61]
	v_lshl_add_u64 v[148:149], v[148:149], 0, s[26:27]
	v_lshl_add_u64 v[148:149], v[148:149], 0, v[0:1]
	v_add_u32_e32 v141, 0x90, v140
	global_store_dwordx4 v[148:149], v[62:65], off
	global_store_dwordx4 v[148:149], v[58:61], off offset:64
	global_store_dwordx4 v[148:149], v[54:57], off offset:512
	global_store_dwordx4 v[148:149], v[46:49], off offset:576
	v_mad_i64_i32 v[148:149], s[62:63], v141, s45, v[146:147]
	v_lshl_add_u64 v[148:149], v[148:149], 0, s[60:61]
	v_lshl_add_u64 v[148:149], v[148:149], 0, s[26:27]
	v_lshl_add_u64 v[148:149], v[148:149], 0, v[0:1]
	v_add_u32_e32 v141, 0xa0, v140
	global_store_dwordx4 v[148:149], v[50:53], off
	global_store_dwordx4 v[148:149], v[42:45], off offset:64
	global_store_dwordx4 v[148:149], v[38:41], off offset:512
	global_store_dwordx4 v[148:149], v[30:33], off offset:576
	v_mad_i64_i32 v[148:149], s[62:63], v141, s45, v[146:147]
	v_add_u32_e32 v141, 0xb0, v140
	v_mad_i64_i32 v[146:147], s[62:63], v141, s45, v[146:147]
	v_lshl_add_u64 v[148:149], v[148:149], 0, s[60:61]
	v_lshl_add_u64 v[146:147], v[146:147], 0, s[60:61]
	v_lshl_add_u64 v[148:149], v[148:149], 0, s[26:27]
	v_lshl_add_u64 v[146:147], v[146:147], 0, s[26:27]
	v_lshl_add_u64 v[148:149], v[148:149], 0, v[0:1]
	v_lshl_add_u64 v[146:147], v[146:147], 0, v[0:1]
	global_store_dwordx4 v[148:149], v[34:37], off
	global_store_dwordx4 v[148:149], v[26:29], off offset:64
	global_store_dwordx4 v[148:149], v[22:25], off offset:512
	global_store_dwordx4 v[148:149], v[14:17], off offset:576
	global_store_dwordx4 v[146:147], v[18:21], off
	global_store_dwordx4 v[146:147], v[10:13], off offset:64
	global_store_dwordx4 v[146:147], v[6:9], off offset:512
	global_store_dwordx4 v[146:147], v[2:5], off offset:576
	s_cbranch_execz .LBB0_258

.LBB0_258:
	s_and_b32 s26, s53, -4
	s_cmp_eq_u32 s26, 4
	s_cselect_b64 vcc, -1, 0
	s_lshl_b32 s52, s53, 8
	v_ashrrev_i32_e32 v141, 31, v140
	s_ashr_i32 s53, s52, 31
	v_lshlrev_b64 v[146:147], 13, v[140:141]
	v_lshl_add_u64 v[146:147], s[24:25], 0, v[146:147]
	s_lshl_b64 s[52:53], s[52:53], 1
	v_mov_b32_e32 v0, 0x3db504f3
	v_lshl_add_u64 v[146:147], v[146:147], 0, s[52:53]
	s_lshl_b32 s26, s68, 1
	v_cndmask_b32_e32 v142, 1.0, v0, vcc
	v_lshl_add_u64 v[146:147], v[146:147], 0, s[26:27]
	v_lshlrev_b32_e32 v0, 1, v134
	v_lshl_add_u64 v[146:147], v[146:147], 0, v[0:1]
	v_pk_mul_f32 v[126:127], v[142:143], v[126:127] op_sel_hi:[0,1]
	v_pk_mul_f32 v[122:123], v[142:143], v[122:123] op_sel_hi:[0,1]
	v_pk_mul_f32 v[118:119], v[142:143], v[118:119] op_sel_hi:[0,1]
	v_pk_mul_f32 v[110:111], v[142:143], v[110:111] op_sel_hi:[0,1]
	v_pk_mul_f32 v[128:129], v[142:143], v[128:129] op_sel_hi:[0,1]
	v_cvt_pk_bf16_f32 v126, v126, v127
	v_cvt_pk_bf16_f32 v127, v128, v129
	global_store_dwordx2 v[146:147], v[126:127], off
	v_pk_mul_f32 v[124:125], v[142:143], v[124:125] op_sel_hi:[0,1]
	v_cvt_pk_bf16_f32 v122, v122, v123
	v_cvt_pk_bf16_f32 v123, v124, v125
	global_store_dwordx2 v[146:147], v[122:123], off offset:32
	v_pk_mul_f32 v[120:121], v[142:143], v[120:121] op_sel_hi:[0,1]
	v_cvt_pk_bf16_f32 v118, v118, v119
	v_cvt_pk_bf16_f32 v119, v120, v121
	global_store_dwordx2 v[146:147], v[118:119], off offset:256
	v_cvt_pk_bf16_f32 v110, v110, v111
	v_pk_mul_f32 v[112:113], v[142:143], v[112:113] op_sel_hi:[0,1]
	v_cvt_pk_bf16_f32 v111, v112, v113
	global_store_dwordx2 v[146:147], v[110:111], off offset:288
	v_or_b32_e32 v110, 16, v140
	v_ashrrev_i32_e32 v111, 31, v110
	v_lshlrev_b64 v[110:111], 13, v[110:111]
	v_lshl_add_u64 v[110:111], s[24:25], 0, v[110:111]
	v_lshl_add_u64 v[110:111], v[110:111], 0, s[52:53]
	v_lshl_add_u64 v[110:111], v[110:111], 0, s[26:27]
	v_lshl_add_u64 v[110:111], v[110:111], 0, v[0:1]
	v_pk_mul_f32 v[114:115], v[142:143], v[114:115] op_sel_hi:[0,1]
	v_pk_mul_f32 v[106:107], v[142:143], v[106:107] op_sel_hi:[0,1]
	v_pk_mul_f32 v[102:103], v[142:143], v[102:103] op_sel_hi:[0,1]
	v_pk_mul_f32 v[94:95], v[142:143], v[94:95] op_sel_hi:[0,1]
	v_pk_mul_f32 v[112:113], v[142:143], v[116:117] op_sel_hi:[0,1]
	v_cvt_pk_bf16_f32 v114, v114, v115
	v_cvt_pk_bf16_f32 v115, v112, v113
	global_store_dwordx2 v[110:111], v[114:115], off
	v_pk_mul_f32 v[108:109], v[142:143], v[108:109] op_sel_hi:[0,1]
	v_cvt_pk_bf16_f32 v106, v106, v107
	v_cvt_pk_bf16_f32 v107, v108, v109
	global_store_dwordx2 v[110:111], v[106:107], off offset:32
	v_pk_mul_f32 v[104:105], v[142:143], v[104:105] op_sel_hi:[0,1]
	v_cvt_pk_bf16_f32 v102, v102, v103
	v_cvt_pk_bf16_f32 v103, v104, v105
	global_store_dwordx2 v[110:111], v[102:103], off offset:256
	v_cvt_pk_bf16_f32 v94, v94, v95
	v_pk_mul_f32 v[96:97], v[142:143], v[96:97] op_sel_hi:[0,1]
	v_cvt_pk_bf16_f32 v95, v96, v97
	global_store_dwordx2 v[110:111], v[94:95], off offset:288
	v_or_b32_e32 v94, 32, v140
	v_ashrrev_i32_e32 v95, 31, v94
	v_lshlrev_b64 v[94:95], 13, v[94:95]
	v_lshl_add_u64 v[94:95], s[24:25], 0, v[94:95]
	v_lshl_add_u64 v[94:95], v[94:95], 0, s[52:53]
	v_lshl_add_u64 v[94:95], v[94:95], 0, s[26:27]
	v_lshl_add_u64 v[94:95], v[94:95], 0, v[0:1]
	v_pk_mul_f32 v[98:99], v[142:143], v[98:99] op_sel_hi:[0,1]
	v_pk_mul_f32 v[90:91], v[142:143], v[90:91] op_sel_hi:[0,1]
	v_pk_mul_f32 v[86:87], v[142:143], v[86:87] op_sel_hi:[0,1]
	v_pk_mul_f32 v[78:79], v[142:143], v[78:79] op_sel_hi:[0,1]
	v_pk_mul_f32 v[96:97], v[142:143], v[100:101] op_sel_hi:[0,1]
	v_cvt_pk_bf16_f32 v98, v98, v99
	v_cvt_pk_bf16_f32 v99, v96, v97
	global_store_dwordx2 v[94:95], v[98:99], off
	v_pk_mul_f32 v[92:93], v[142:143], v[92:93] op_sel_hi:[0,1]
	v_cvt_pk_bf16_f32 v90, v90, v91
	v_cvt_pk_bf16_f32 v91, v92, v93
	global_store_dwordx2 v[94:95], v[90:91], off offset:32
	v_pk_mul_f32 v[88:89], v[142:143], v[88:89] op_sel_hi:[0,1]
	v_cvt_pk_bf16_f32 v86, v86, v87
	v_cvt_pk_bf16_f32 v87, v88, v89
	global_store_dwordx2 v[94:95], v[86:87], off offset:256
	v_cvt_pk_bf16_f32 v78, v78, v79
	v_pk_mul_f32 v[80:81], v[142:143], v[80:81] op_sel_hi:[0,1]
	v_cvt_pk_bf16_f32 v79, v80, v81
	global_store_dwordx2 v[94:95], v[78:79], off offset:288
	v_or_b32_e32 v78, 48, v140
	v_ashrrev_i32_e32 v79, 31, v78
	v_lshlrev_b64 v[78:79], 13, v[78:79]
	v_lshl_add_u64 v[78:79], s[24:25], 0, v[78:79]
	v_lshl_add_u64 v[78:79], v[78:79], 0, s[52:53]
	v_lshl_add_u64 v[78:79], v[78:79], 0, s[26:27]
	v_lshl_add_u64 v[78:79], v[78:79], 0, v[0:1]
	v_pk_mul_f32 v[82:83], v[142:143], v[82:83] op_sel_hi:[0,1]
	v_pk_mul_f32 v[74:75], v[142:143], v[74:75] op_sel_hi:[0,1]
	v_pk_mul_f32 v[70:71], v[142:143], v[70:71] op_sel_hi:[0,1]
	v_pk_mul_f32 v[66:67], v[142:143], v[66:67] op_sel_hi:[0,1]
	v_pk_mul_f32 v[80:81], v[142:143], v[84:85] op_sel_hi:[0,1]
	v_cvt_pk_bf16_f32 v82, v82, v83
	v_cvt_pk_bf16_f32 v83, v80, v81
	global_store_dwordx2 v[78:79], v[82:83], off
	v_pk_mul_f32 v[76:77], v[142:143], v[76:77] op_sel_hi:[0,1]
	v_cvt_pk_bf16_f32 v74, v74, v75
	v_cvt_pk_bf16_f32 v75, v76, v77
	global_store_dwordx2 v[78:79], v[74:75], off offset:32
	v_pk_mul_f32 v[72:73], v[142:143], v[72:73] op_sel_hi:[0,1]
	v_cvt_pk_bf16_f32 v70, v70, v71
	v_cvt_pk_bf16_f32 v71, v72, v73
	global_store_dwordx2 v[78:79], v[70:71], off offset:256
	v_cvt_pk_bf16_f32 v66, v66, v67
	v_pk_mul_f32 v[68:69], v[142:143], v[68:69] op_sel_hi:[0,1]
	v_cvt_pk_bf16_f32 v67, v68, v69
	global_store_dwordx2 v[78:79], v[66:67], off offset:288
	v_add_u32_e32 v66, 0x80, v140
	v_ashrrev_i32_e32 v67, 31, v66
	v_lshlrev_b64 v[66:67], 13, v[66:67]
	v_lshl_add_u64 v[66:67], s[24:25], 0, v[66:67]
	v_lshl_add_u64 v[66:67], v[66:67], 0, s[52:53]
	v_lshl_add_u64 v[66:67], v[66:67], 0, s[26:27]
	v_lshl_add_u64 v[66:67], v[66:67], 0, v[0:1]
	v_pk_mul_f32 v[62:63], v[142:143], v[62:63] op_sel_hi:[0,1]
	v_pk_mul_f32 v[58:59], v[142:143], v[58:59] op_sel_hi:[0,1]
	v_pk_mul_f32 v[54:55], v[142:143], v[54:55] op_sel_hi:[0,1]
	v_pk_mul_f32 v[46:47], v[142:143], v[46:47] op_sel_hi:[0,1]
	v_pk_mul_f32 v[64:65], v[142:143], v[64:65] op_sel_hi:[0,1]
	v_cvt_pk_bf16_f32 v62, v62, v63
	v_cvt_pk_bf16_f32 v63, v64, v65
	global_store_dwordx2 v[66:67], v[62:63], off
	v_pk_mul_f32 v[60:61], v[142:143], v[60:61] op_sel_hi:[0,1]
	v_cvt_pk_bf16_f32 v58, v58, v59
	v_cvt_pk_bf16_f32 v59, v60, v61
	global_store_dwordx2 v[66:67], v[58:59], off offset:32
	v_pk_mul_f32 v[56:57], v[142:143], v[56:57] op_sel_hi:[0,1]
	v_cvt_pk_bf16_f32 v54, v54, v55
	v_cvt_pk_bf16_f32 v55, v56, v57
	global_store_dwordx2 v[66:67], v[54:55], off offset:256
	v_cvt_pk_bf16_f32 v46, v46, v47
	v_pk_mul_f32 v[48:49], v[142:143], v[48:49] op_sel_hi:[0,1]
	v_cvt_pk_bf16_f32 v47, v48, v49
	global_store_dwordx2 v[66:67], v[46:47], off offset:288
	v_add_u32_e32 v46, 0x90, v140
	v_ashrrev_i32_e32 v47, 31, v46
	v_lshlrev_b64 v[46:47], 13, v[46:47]
	v_lshl_add_u64 v[46:47], s[24:25], 0, v[46:47]
	v_lshl_add_u64 v[46:47], v[46:47], 0, s[52:53]
	v_lshl_add_u64 v[46:47], v[46:47], 0, s[26:27]
	v_lshl_add_u64 v[46:47], v[46:47], 0, v[0:1]
	v_pk_mul_f32 v[50:51], v[142:143], v[50:51] op_sel_hi:[0,1]
	v_pk_mul_f32 v[42:43], v[142:143], v[42:43] op_sel_hi:[0,1]
	v_pk_mul_f32 v[38:39], v[142:143], v[38:39] op_sel_hi:[0,1]
	v_pk_mul_f32 v[30:31], v[142:143], v[30:31] op_sel_hi:[0,1]
	v_pk_mul_f32 v[48:49], v[142:143], v[52:53] op_sel_hi:[0,1]
	v_cvt_pk_bf16_f32 v50, v50, v51
	v_cvt_pk_bf16_f32 v51, v48, v49
	global_store_dwordx2 v[46:47], v[50:51], off
	v_pk_mul_f32 v[44:45], v[142:143], v[44:45] op_sel_hi:[0,1]
	v_cvt_pk_bf16_f32 v42, v42, v43
	v_cvt_pk_bf16_f32 v43, v44, v45
	global_store_dwordx2 v[46:47], v[42:43], off offset:32
	v_pk_mul_f32 v[40:41], v[142:143], v[40:41] op_sel_hi:[0,1]
	v_cvt_pk_bf16_f32 v38, v38, v39
	v_cvt_pk_bf16_f32 v39, v40, v41
	global_store_dwordx2 v[46:47], v[38:39], off offset:256
	v_cvt_pk_bf16_f32 v30, v30, v31
	v_pk_mul_f32 v[32:33], v[142:143], v[32:33] op_sel_hi:[0,1]
	v_cvt_pk_bf16_f32 v31, v32, v33
	global_store_dwordx2 v[46:47], v[30:31], off offset:288
	v_add_u32_e32 v30, 0xa0, v140
	v_ashrrev_i32_e32 v31, 31, v30
	v_lshlrev_b64 v[30:31], 13, v[30:31]
	v_lshl_add_u64 v[30:31], s[24:25], 0, v[30:31]
	v_lshl_add_u64 v[30:31], v[30:31], 0, s[52:53]
	v_lshl_add_u64 v[30:31], v[30:31], 0, s[26:27]
	v_lshl_add_u64 v[30:31], v[30:31], 0, v[0:1]
	v_pk_mul_f32 v[34:35], v[142:143], v[34:35] op_sel_hi:[0,1]
	v_pk_mul_f32 v[26:27], v[142:143], v[26:27] op_sel_hi:[0,1]
	v_pk_mul_f32 v[22:23], v[142:143], v[22:23] op_sel_hi:[0,1]
	v_pk_mul_f32 v[14:15], v[142:143], v[14:15] op_sel_hi:[0,1]
	v_pk_mul_f32 v[32:33], v[142:143], v[36:37] op_sel_hi:[0,1]
	v_cvt_pk_bf16_f32 v34, v34, v35
	v_cvt_pk_bf16_f32 v35, v32, v33
	global_store_dwordx2 v[30:31], v[34:35], off
	v_pk_mul_f32 v[28:29], v[142:143], v[28:29] op_sel_hi:[0,1]
	v_cvt_pk_bf16_f32 v26, v26, v27
	v_cvt_pk_bf16_f32 v27, v28, v29
	global_store_dwordx2 v[30:31], v[26:27], off offset:32
	v_pk_mul_f32 v[24:25], v[142:143], v[24:25] op_sel_hi:[0,1]
	v_cvt_pk_bf16_f32 v22, v22, v23
	v_cvt_pk_bf16_f32 v23, v24, v25
	global_store_dwordx2 v[30:31], v[22:23], off offset:256
	v_cvt_pk_bf16_f32 v14, v14, v15
	v_pk_mul_f32 v[16:17], v[142:143], v[16:17] op_sel_hi:[0,1]
	v_cvt_pk_bf16_f32 v15, v16, v17
	global_store_dwordx2 v[30:31], v[14:15], off offset:288
	v_add_u32_e32 v14, 0xb0, v140
	v_ashrrev_i32_e32 v15, 31, v14
	v_lshlrev_b64 v[14:15], 13, v[14:15]
	v_lshl_add_u64 v[14:15], s[24:25], 0, v[14:15]
	v_lshl_add_u64 v[14:15], v[14:15], 0, s[52:53]
	v_lshl_add_u64 v[14:15], v[14:15], 0, s[26:27]
	v_lshl_add_u64 v[14:15], v[14:15], 0, v[0:1]
	v_pk_mul_f32 v[18:19], v[142:143], v[18:19] op_sel_hi:[0,1]
	v_pk_mul_f32 v[10:11], v[142:143], v[10:11] op_sel_hi:[0,1]
	v_pk_mul_f32 v[6:7], v[142:143], v[6:7] op_sel_hi:[0,1]
	v_pk_mul_f32 v[2:3], v[142:143], v[2:3] op_sel_hi:[0,1]
	v_pk_mul_f32 v[16:17], v[142:143], v[20:21] op_sel_hi:[0,1]
	v_cvt_pk_bf16_f32 v18, v18, v19
	v_cvt_pk_bf16_f32 v19, v16, v17
	global_store_dwordx2 v[14:15], v[18:19], off
	v_pk_mul_f32 v[12:13], v[142:143], v[12:13] op_sel_hi:[0,1]
	v_cvt_pk_bf16_f32 v10, v10, v11
	v_cvt_pk_bf16_f32 v11, v12, v13
	global_store_dwordx2 v[14:15], v[10:11], off offset:32
	v_pk_mul_f32 v[8:9], v[142:143], v[8:9] op_sel_hi:[0,1]
	v_cvt_pk_bf16_f32 v6, v6, v7
	v_cvt_pk_bf16_f32 v7, v8, v9
	global_store_dwordx2 v[14:15], v[6:7], off offset:256
	v_pk_mul_f32 v[4:5], v[142:143], v[4:5] op_sel_hi:[0,1]
	v_cvt_pk_bf16_f32 v2, v2, v3
	v_cvt_pk_bf16_f32 v3, v4, v5
	global_store_dwordx2 v[14:15], v[2:3], off offset:288
	s_andn2_b64 vcc, exec, s[38:39]
	s_mov_b64 s[38:39], -1
	s_cbranch_vccnz .LBB0_247

.LBB0_332:
	s_add_u32 s52, s52, s71
	s_addc_u32 s53, s53, 0
	v_lshl_add_u64 v[158:159], s[52:53], 0, v[0:1]
	v_mad_i64_i32 v[160:161], s[52:53], s46, v138, 0
	v_lshl_add_u64 v[160:161], v[160:161], 1, v[158:159]
	v_cvt_pk_bf16_f32 v126, v126, v127
	v_cvt_pk_bf16_f32 v127, v128, v129
	v_cvt_pk_bf16_f32 v128, v122, v123
	v_cvt_pk_bf16_f32 v129, v124, v125
	global_store_dwordx4 v[160:161], v[126:129], off
	v_cvt_pk_bf16_f32 v114, v114, v115
	v_cvt_pk_bf16_f32 v115, v116, v117
	v_cvt_pk_bf16_f32 v116, v106, v107
	v_mad_i64_i32 v[106:107], s[52:53], s46, v140, 0
	v_cvt_pk_bf16_f32 v117, v108, v109
	global_store_dwordx4 v[160:161], v[114:117], off offset:256
	s_andn2_b64 vcc, exec, s[38:39]
	s_mov_b64 s[38:39], -1
	v_lshl_add_u64 v[114:115], v[106:107], 1, v[158:159]
	v_cvt_pk_bf16_f32 v106, v118, v119
	v_cvt_pk_bf16_f32 v107, v120, v121
	v_cvt_pk_bf16_f32 v108, v110, v111
	v_cvt_pk_bf16_f32 v109, v112, v113
	global_store_dwordx4 v[114:115], v[106:109], off
	v_cvt_pk_bf16_f32 v98, v98, v99
	v_cvt_pk_bf16_f32 v99, v100, v101
	v_cvt_pk_bf16_f32 v100, v90, v91
	v_mad_i64_i32 v[90:91], s[52:53], s46, v142, 0
	v_cvt_pk_bf16_f32 v101, v92, v93
	global_store_dwordx4 v[114:115], v[98:101], off offset:256
	s_nop 1
	v_lshl_add_u64 v[98:99], v[90:91], 1, v[158:159]
	v_cvt_pk_bf16_f32 v90, v102, v103
	v_cvt_pk_bf16_f32 v91, v104, v105
	v_cvt_pk_bf16_f32 v92, v94, v95
	v_cvt_pk_bf16_f32 v93, v96, v97
	global_store_dwordx4 v[98:99], v[90:93], off
	v_cvt_pk_bf16_f32 v82, v82, v83
	v_cvt_pk_bf16_f32 v83, v84, v85
	v_cvt_pk_bf16_f32 v84, v74, v75
	v_mad_i64_i32 v[74:75], s[52:53], s46, v144, 0
	v_cvt_pk_bf16_f32 v85, v76, v77
	global_store_dwordx4 v[98:99], v[82:85], off offset:256
	s_nop 1
	v_lshl_add_u64 v[82:83], v[74:75], 1, v[158:159]
	v_cvt_pk_bf16_f32 v74, v86, v87
	v_cvt_pk_bf16_f32 v75, v88, v89
	v_cvt_pk_bf16_f32 v76, v78, v79
	v_cvt_pk_bf16_f32 v77, v80, v81
	global_store_dwordx4 v[82:83], v[74:77], off
	v_cvt_pk_bf16_f32 v70, v70, v71
	v_cvt_pk_bf16_f32 v71, v72, v73
	v_cvt_pk_bf16_f32 v72, v66, v67
	v_mad_i64_i32 v[66:67], s[52:53], s46, v146, 0
	v_lshl_add_u64 v[66:67], v[66:67], 1, v[158:159]
	v_cvt_pk_bf16_f32 v73, v68, v69
	global_store_dwordx4 v[82:83], v[70:73], off offset:256
	v_cvt_pk_bf16_f32 v62, v62, v63
	v_cvt_pk_bf16_f32 v63, v64, v65
	v_cvt_pk_bf16_f32 v64, v58, v59
	v_cvt_pk_bf16_f32 v65, v60, v61
	global_store_dwordx4 v[66:67], v[62:65], off
	v_cvt_pk_bf16_f32 v50, v50, v51
	v_cvt_pk_bf16_f32 v51, v52, v53
	v_cvt_pk_bf16_f32 v52, v42, v43
	v_mad_i64_i32 v[42:43], s[52:53], s46, v148, 0
	v_cvt_pk_bf16_f32 v53, v44, v45
	global_store_dwordx4 v[66:67], v[50:53], off offset:256
	s_nop 1
	v_lshl_add_u64 v[50:51], v[42:43], 1, v[158:159]
	v_cvt_pk_bf16_f32 v42, v54, v55
	v_cvt_pk_bf16_f32 v43, v56, v57
	v_cvt_pk_bf16_f32 v44, v46, v47
	v_cvt_pk_bf16_f32 v45, v48, v49
	global_store_dwordx4 v[50:51], v[42:45], off
	v_cvt_pk_bf16_f32 v34, v34, v35
	v_cvt_pk_bf16_f32 v35, v36, v37
	v_cvt_pk_bf16_f32 v36, v26, v27
	v_mad_i64_i32 v[26:27], s[52:53], s46, v150, 0
	v_cvt_pk_bf16_f32 v37, v28, v29
	global_store_dwordx4 v[50:51], v[34:37], off offset:256
	s_nop 1
	v_lshl_add_u64 v[34:35], v[26:27], 1, v[158:159]
	v_cvt_pk_bf16_f32 v26, v38, v39
	v_cvt_pk_bf16_f32 v27, v40, v41
	v_cvt_pk_bf16_f32 v28, v30, v31
	v_cvt_pk_bf16_f32 v29, v32, v33
	global_store_dwordx4 v[34:35], v[26:29], off
	v_cvt_pk_bf16_f32 v18, v18, v19
	v_cvt_pk_bf16_f32 v19, v20, v21
	v_cvt_pk_bf16_f32 v20, v10, v11
	v_mad_i64_i32 v[10:11], s[46:47], s46, v152, 0
	v_cvt_pk_bf16_f32 v21, v12, v13
	global_store_dwordx4 v[34:35], v[18:21], off offset:256
	s_nop 1
	v_lshl_add_u64 v[18:19], v[10:11], 1, v[158:159]
	v_cvt_pk_bf16_f32 v10, v22, v23
	v_cvt_pk_bf16_f32 v11, v24, v25
	v_cvt_pk_bf16_f32 v12, v14, v15
	v_cvt_pk_bf16_f32 v13, v16, v17
	global_store_dwordx4 v[18:19], v[10:13], off
	v_cvt_pk_bf16_f32 v6, v6, v7
	v_cvt_pk_bf16_f32 v7, v8, v9
	v_cvt_pk_bf16_f32 v8, v2, v3
	v_cvt_pk_bf16_f32 v9, v4, v5
	global_store_dwordx4 v[18:19], v[6:9], off offset:256
	s_cbranch_vccnz .LBB0_318
	s_andn2_b64 vcc, exec, s[0:1]
	s_cbranch_vccnz .LBB0_317
	s_barrier
	s_branch .LBB0_317

.LBB0_390:
	s_lshl_b32 s52, s68, 8
	v_lshl_add_u32 v141, s40, 8, v138
	s_ashr_i32 s53, s52, 31
	v_mov_b64_e32 v[142:143], s[24:25]
	v_mad_i64_i32 v[144:145], s[60:61], v141, s16, v[142:143]
	s_lshl_b64 s[52:53], s[52:53], 2
	v_lshl_add_u64 v[144:145], v[144:145], 0, s[52:53]
	v_lshl_add_u64 v[144:145], v[144:145], 0, s[26:27]
	v_lshl_add_u64 v[144:145], v[144:145], 0, v[0:1]
	global_store_dwordx4 v[144:145], v[126:129], off
	global_store_dwordx4 v[144:145], v[122:125], off offset:64
	global_store_dwordx4 v[144:145], v[106:109], off offset:512
	global_store_dwordx4 v[144:145], v[98:101], off offset:576
	v_readlane_b32 s80, v254, 35
	s_andn2_b64 vcc, exec, s[38:39]
	v_or_b32_e32 v98, 16, v141
	v_mad_i64_i32 v[98:99], s[60:61], v98, s16, v[142:143]
	v_lshl_add_u64 v[98:99], v[98:99], 0, s[52:53]
	v_lshl_add_u64 v[98:99], v[98:99], 0, s[26:27]
	v_lshl_add_u64 v[98:99], v[98:99], 0, v[0:1]
	global_store_dwordx4 v[98:99], v[118:121], off
	global_store_dwordx4 v[98:99], v[114:117], off offset:64
	global_store_dwordx4 v[98:99], v[90:93], off offset:512
	global_store_dwordx4 v[98:99], v[82:85], off offset:576
	s_mov_b64 s[38:39], -1
	v_readlane_b32 s81, v254, 36
	v_or_b32_e32 v82, 32, v141
	v_mad_i64_i32 v[82:83], s[60:61], v82, s16, v[142:143]
	v_lshl_add_u64 v[82:83], v[82:83], 0, s[52:53]
	v_lshl_add_u64 v[82:83], v[82:83], 0, s[26:27]
	v_lshl_add_u64 v[82:83], v[82:83], 0, v[0:1]
	global_store_dwordx4 v[82:83], v[110:113], off
	global_store_dwordx4 v[82:83], v[102:105], off offset:64
	global_store_dwordx4 v[82:83], v[78:81], off offset:512
	global_store_dwordx4 v[82:83], v[74:77], off offset:576
	v_readlane_b32 s82, v254, 37
	v_readlane_b32 s83, v254, 38
	v_or_b32_e32 v74, 48, v141
	v_mad_i64_i32 v[74:75], s[60:61], v74, s16, v[142:143]
	v_lshl_add_u64 v[74:75], v[74:75], 0, s[52:53]
	v_lshl_add_u64 v[74:75], v[74:75], 0, s[26:27]
	v_lshl_add_u64 v[74:75], v[74:75], 0, v[0:1]
	global_store_dwordx4 v[74:75], v[94:97], off
	global_store_dwordx4 v[74:75], v[86:89], off offset:64
	global_store_dwordx4 v[74:75], v[70:73], off offset:512
	global_store_dwordx4 v[74:75], v[66:69], off offset:576
	v_readlane_b32 s84, v254, 39
	v_readlane_b32 s85, v254, 40
	v_add_u32_e32 v66, 0x80, v141
	v_mad_i64_i32 v[66:67], s[60:61], v66, s16, v[142:143]
	v_lshl_add_u64 v[66:67], v[66:67], 0, s[52:53]
	v_lshl_add_u64 v[66:67], v[66:67], 0, s[26:27]
	v_lshl_add_u64 v[66:67], v[66:67], 0, v[0:1]
	global_store_dwordx4 v[66:67], v[62:65], off
	global_store_dwordx4 v[66:67], v[58:61], off offset:64
	global_store_dwordx4 v[66:67], v[42:45], off offset:512
	global_store_dwordx4 v[66:67], v[34:37], off offset:576
	v_readlane_b32 s86, v254, 41
	v_readlane_b32 s87, v254, 42
	v_add_u32_e32 v34, 0x90, v141
	v_mad_i64_i32 v[34:35], s[60:61], v34, s16, v[142:143]
	v_lshl_add_u64 v[34:35], v[34:35], 0, s[52:53]
	v_lshl_add_u64 v[34:35], v[34:35], 0, s[26:27]
	v_lshl_add_u64 v[34:35], v[34:35], 0, v[0:1]
	global_store_dwordx4 v[34:35], v[54:57], off
	global_store_dwordx4 v[34:35], v[50:53], off offset:64
	global_store_dwordx4 v[34:35], v[26:29], off offset:512
	global_store_dwordx4 v[34:35], v[18:21], off offset:576
	v_readlane_b32 s88, v254, 43
	v_readlane_b32 s89, v254, 44
	v_add_u32_e32 v18, 0xa0, v141
	v_mad_i64_i32 v[18:19], s[60:61], v18, s16, v[142:143]
	v_lshl_add_u64 v[18:19], v[18:19], 0, s[52:53]
	v_lshl_add_u64 v[18:19], v[18:19], 0, s[26:27]
	v_lshl_add_u64 v[18:19], v[18:19], 0, v[0:1]
	global_store_dwordx4 v[18:19], v[46:49], off
	global_store_dwordx4 v[18:19], v[38:41], off offset:64
	global_store_dwordx4 v[18:19], v[14:17], off offset:512
	global_store_dwordx4 v[18:19], v[10:13], off offset:576
	v_readlane_b32 s90, v254, 45
	v_readlane_b32 s91, v254, 46
	v_add_u32_e32 v10, 0xb0, v141
	v_mad_i64_i32 v[10:11], s[60:61], v10, s16, v[142:143]
	v_lshl_add_u64 v[10:11], v[10:11], 0, s[52:53]
	v_lshl_add_u64 v[10:11], v[10:11], 0, s[26:27]
	v_lshl_add_u64 v[10:11], v[10:11], 0, v[0:1]
	v_readlane_b32 s92, v254, 47
	v_readlane_b32 s93, v254, 48
	v_readlane_b32 s94, v254, 49
	v_readlane_b32 s95, v254, 50
	global_store_dwordx4 v[10:11], v[30:33], off
	global_store_dwordx4 v[10:11], v[22:25], off offset:64
	global_store_dwordx4 v[10:11], v[6:9], off offset:512
	global_store_dwordx4 v[10:11], v[2:5], off offset:576
	s_cbranch_vccnz .LBB0_383
	s_andn2_b64 vcc, exec, s[0:1]
	s_cbranch_vccnz .LBB0_382
	s_barrier
	s_branch .LBB0_382

.LBB0_435:
	v_mul_f32_e32 v176, 0xbfb8aa3b, v126
	v_mul_f32_e32 v177, 0xbfb8aa3b, v127
	v_mul_f32_e32 v178, 0xbfb8aa3b, v128
	v_mul_f32_e32 v179, 0xbfb8aa3b, v129
	v_mul_f32_e32 v180, 0xbfb8aa3b, v118
	v_mul_f32_e32 v181, 0xbfb8aa3b, v119
	v_mul_f32_e32 v182, 0xbfb8aa3b, v120
	v_mul_f32_e32 v183, 0xbfb8aa3b, v121
	v_exp_f32_e32 v176, v176
	v_exp_f32_e32 v177, v177
	v_exp_f32_e32 v178, v178
	v_exp_f32_e32 v179, v179
	v_exp_f32_e32 v180, v180
	v_exp_f32_e32 v181, v181
	v_exp_f32_e32 v182, v182
	v_exp_f32_e32 v183, v183
	v_add_f32_e32 v176, 1.0, v176
	v_add_f32_e32 v177, 1.0, v177
	v_add_f32_e32 v178, 1.0, v178
	v_add_f32_e32 v179, 1.0, v179
	v_add_f32_e32 v180, 1.0, v180
	v_add_f32_e32 v181, 1.0, v181
	v_add_f32_e32 v182, 1.0, v182
	v_add_f32_e32 v183, 1.0, v183
	v_rcp_f32_e32 v176, v176
	v_rcp_f32_e32 v177, v177
	v_rcp_f32_e32 v178, v178
	v_rcp_f32_e32 v179, v179
	v_rcp_f32_e32 v180, v180
	v_rcp_f32_e32 v181, v181
	v_rcp_f32_e32 v182, v182
	v_rcp_f32_e32 v183, v183
	v_mul_f32_e32 v176, v126, v176
	v_mul_f32_e32 v177, v127, v177
	v_mul_f32_e32 v178, v128, v178
	v_mul_f32_e32 v179, v129, v179
	v_mul_f32_e32 v180, v118, v180
	v_mul_f32_e32 v181, v119, v181
	v_mul_f32_e32 v182, v120, v182
	v_mul_f32_e32 v183, v121, v183
	s_lshl_b32 s6, s48, 8
	v_add_u32_e32 v154, s6, v144
	v_mov_b64_e32 v[142:143], s[22:23]
	v_mad_i64_i32 v[154:155], s[48:49], v154, s16, v[142:143]
	s_lshl_b32 s48, s9, 7
	v_mul_f32_e32 v122, v176, v122
	s_ashr_i32 s49, s48, 31
	s_lshl_b64 s[48:49], s[48:49], 1
	v_lshl_add_u64 v[154:155], v[154:155], 0, s[48:49]
	v_lshl_add_u64 v[154:155], v[154:155], 0, s[26:27]
	v_readlane_b32 s80, v254, 35
	s_andn2_b64 vcc, exec, s[38:39]
	v_mul_f32_e32 v123, v177, v123
	v_readlane_b32 s81, v254, 36
	v_readlane_b32 s82, v254, 37
	v_readlane_b32 s83, v254, 38
	v_readlane_b32 s84, v254, 39
	v_readlane_b32 s85, v254, 40
	v_readlane_b32 s86, v254, 41
	v_mul_f32_e32 v124, v178, v124
	v_readlane_b32 s87, v254, 42
	v_readlane_b32 s88, v254, 43
	v_readlane_b32 s89, v254, 44
	v_readlane_b32 s90, v254, 45
	v_readlane_b32 s91, v254, 46
	v_readlane_b32 s92, v254, 47
	v_mul_f32_e32 v125, v179, v125
	v_readlane_b32 s93, v254, 48
	v_readlane_b32 s94, v254, 49
	v_readlane_b32 s95, v254, 50
	v_mul_f32_e32 v126, v180, v114
	v_mul_f32_e32 v127, v181, v115
	v_lshl_add_u64 v[118:119], v[154:155], 0, v[0:1]
	v_mul_f32_e32 v120, v182, v116
	v_mul_f32_e32 v117, v183, v117
	v_cvt_pk_bf16_f32 v114, v122, v123
	v_cvt_pk_bf16_f32 v115, v124, v125
	v_cvt_pk_bf16_f32 v116, v126, v127
	v_cvt_pk_bf16_f32 v117, v120, v117
	global_store_dwordx4 v[118:119], v[114:117], off
	s_nop 1
	v_mul_f32_e32 v176, 0xbfb8aa3b, v110
	v_mul_f32_e32 v177, 0xbfb8aa3b, v111
	v_mul_f32_e32 v178, 0xbfb8aa3b, v112
	v_mul_f32_e32 v179, 0xbfb8aa3b, v113
	v_mul_f32_e32 v180, 0xbfb8aa3b, v102
	v_mul_f32_e32 v181, 0xbfb8aa3b, v103
	v_mul_f32_e32 v182, 0xbfb8aa3b, v104
	v_mul_f32_e32 v183, 0xbfb8aa3b, v105
	v_exp_f32_e32 v176, v176
	v_exp_f32_e32 v177, v177
	v_exp_f32_e32 v178, v178
	v_exp_f32_e32 v179, v179
	v_exp_f32_e32 v180, v180
	v_exp_f32_e32 v181, v181
	v_exp_f32_e32 v182, v182
	v_exp_f32_e32 v183, v183
	v_add_f32_e32 v176, 1.0, v176
	v_add_f32_e32 v177, 1.0, v177
	v_add_f32_e32 v178, 1.0, v178
	v_add_f32_e32 v179, 1.0, v179
	v_add_f32_e32 v180, 1.0, v180
	v_add_f32_e32 v181, 1.0, v181
	v_add_f32_e32 v182, 1.0, v182
	v_add_f32_e32 v183, 1.0, v183
	v_rcp_f32_e32 v176, v176
	v_rcp_f32_e32 v177, v177
	v_rcp_f32_e32 v178, v178
	v_rcp_f32_e32 v179, v179
	v_rcp_f32_e32 v180, v180
	v_rcp_f32_e32 v181, v181
	v_rcp_f32_e32 v182, v182
	v_rcp_f32_e32 v183, v183
	v_mul_f32_e32 v176, v110, v176
	v_mul_f32_e32 v177, v111, v177
	v_mul_f32_e32 v178, v112, v178
	v_mul_f32_e32 v179, v113, v179
	v_mul_f32_e32 v180, v102, v180
	v_mul_f32_e32 v181, v103, v181
	v_mul_f32_e32 v182, v104, v182
	v_mul_f32_e32 v183, v105, v183
	v_add_u32_e32 v114, s6, v146
	v_mad_i64_i32 v[114:115], s[50:51], v114, s16, v[142:143]
	v_lshl_add_u64 v[114:115], v[114:115], 0, s[48:49]
	v_lshl_add_u64 v[114:115], v[114:115], 0, s[26:27]
	v_mul_f32_e32 v106, v176, v106
	v_mul_f32_e32 v107, v177, v107
	v_mul_f32_e32 v108, v178, v108
	v_mul_f32_e32 v109, v179, v109
	v_mul_f32_e32 v110, v180, v98
	v_mul_f32_e32 v111, v181, v99
	v_lshl_add_u64 v[102:103], v[114:115], 0, v[0:1]
	v_mul_f32_e32 v104, v182, v100
	v_mul_f32_e32 v101, v183, v101
	v_cvt_pk_bf16_f32 v98, v106, v107
	v_cvt_pk_bf16_f32 v99, v108, v109
	v_cvt_pk_bf16_f32 v100, v110, v111
	v_cvt_pk_bf16_f32 v101, v104, v101
	global_store_dwordx4 v[102:103], v[98:101], off
	s_nop 1
	v_mul_f32_e32 v176, 0xbfb8aa3b, v94
	v_mul_f32_e32 v177, 0xbfb8aa3b, v95
	v_mul_f32_e32 v178, 0xbfb8aa3b, v96
	v_mul_f32_e32 v179, 0xbfb8aa3b, v97
	v_mul_f32_e32 v180, 0xbfb8aa3b, v86
	v_mul_f32_e32 v181, 0xbfb8aa3b, v87
	v_mul_f32_e32 v182, 0xbfb8aa3b, v88
	v_mul_f32_e32 v183, 0xbfb8aa3b, v89
	v_exp_f32_e32 v176, v176
	v_exp_f32_e32 v177, v177
	v_exp_f32_e32 v178, v178
	v_exp_f32_e32 v179, v179
	v_exp_f32_e32 v180, v180
	v_exp_f32_e32 v181, v181
	v_exp_f32_e32 v182, v182
	v_exp_f32_e32 v183, v183
	v_add_f32_e32 v176, 1.0, v176
	v_add_f32_e32 v177, 1.0, v177
	v_add_f32_e32 v178, 1.0, v178
	v_add_f32_e32 v179, 1.0, v179
	v_add_f32_e32 v180, 1.0, v180
	v_add_f32_e32 v181, 1.0, v181
	v_add_f32_e32 v182, 1.0, v182
	v_add_f32_e32 v183, 1.0, v183
	v_rcp_f32_e32 v176, v176
	v_rcp_f32_e32 v177, v177
	v_rcp_f32_e32 v178, v178
	v_rcp_f32_e32 v179, v179
	v_rcp_f32_e32 v180, v180
	v_rcp_f32_e32 v181, v181
	v_rcp_f32_e32 v182, v182
	v_rcp_f32_e32 v183, v183
	v_mul_f32_e32 v176, v94, v176
	v_mul_f32_e32 v177, v95, v177
	v_mul_f32_e32 v178, v96, v178
	v_mul_f32_e32 v179, v97, v179
	v_mul_f32_e32 v180, v86, v180
	v_mul_f32_e32 v181, v87, v181
	v_mul_f32_e32 v182, v88, v182
	v_mul_f32_e32 v183, v89, v183
	v_add_u32_e32 v98, s6, v147
	v_mad_i64_i32 v[98:99], s[50:51], v98, s16, v[142:143]
	v_lshl_add_u64 v[98:99], v[98:99], 0, s[48:49]
	v_lshl_add_u64 v[98:99], v[98:99], 0, s[26:27]
	v_mul_f32_e32 v90, v176, v90
	v_mul_f32_e32 v91, v177, v91
	v_mul_f32_e32 v92, v178, v92
	v_mul_f32_e32 v93, v179, v93
	v_mul_f32_e32 v94, v180, v82
	v_mul_f32_e32 v95, v181, v83
	v_lshl_add_u64 v[86:87], v[98:99], 0, v[0:1]
	v_mul_f32_e32 v88, v182, v84
	v_mul_f32_e32 v85, v183, v85
	v_cvt_pk_bf16_f32 v82, v90, v91
	v_cvt_pk_bf16_f32 v83, v92, v93
	v_cvt_pk_bf16_f32 v84, v94, v95
	v_cvt_pk_bf16_f32 v85, v88, v85
	global_store_dwordx4 v[86:87], v[82:85], off
	s_nop 1
	v_mul_f32_e32 v176, 0xbfb8aa3b, v78
	v_mul_f32_e32 v177, 0xbfb8aa3b, v79
	v_mul_f32_e32 v178, 0xbfb8aa3b, v80
	v_mul_f32_e32 v179, 0xbfb8aa3b, v81
	v_mul_f32_e32 v180, 0xbfb8aa3b, v70
	v_mul_f32_e32 v181, 0xbfb8aa3b, v71
	v_mul_f32_e32 v182, 0xbfb8aa3b, v72
	v_mul_f32_e32 v183, 0xbfb8aa3b, v73
	v_exp_f32_e32 v176, v176
	v_exp_f32_e32 v177, v177
	v_exp_f32_e32 v178, v178
	v_exp_f32_e32 v179, v179
	v_exp_f32_e32 v180, v180
	v_exp_f32_e32 v181, v181
	v_exp_f32_e32 v182, v182
	v_exp_f32_e32 v183, v183
	v_add_f32_e32 v176, 1.0, v176
	v_add_f32_e32 v177, 1.0, v177
	v_add_f32_e32 v178, 1.0, v178
	v_add_f32_e32 v179, 1.0, v179
	v_add_f32_e32 v180, 1.0, v180
	v_add_f32_e32 v181, 1.0, v181
	v_add_f32_e32 v182, 1.0, v182
	v_add_f32_e32 v183, 1.0, v183
	v_rcp_f32_e32 v176, v176
	v_rcp_f32_e32 v177, v177
	v_rcp_f32_e32 v178, v178
	v_rcp_f32_e32 v179, v179
	v_rcp_f32_e32 v180, v180
	v_rcp_f32_e32 v181, v181
	v_rcp_f32_e32 v182, v182
	v_rcp_f32_e32 v183, v183
	v_mul_f32_e32 v176, v78, v176
	v_mul_f32_e32 v177, v79, v177
	v_mul_f32_e32 v178, v80, v178
	v_mul_f32_e32 v179, v81, v179
	v_mul_f32_e32 v180, v70, v180
	v_mul_f32_e32 v181, v71, v181
	v_mul_f32_e32 v182, v72, v182
	v_mul_f32_e32 v183, v73, v183
	v_add_u32_e32 v82, s6, v148
	v_mad_i64_i32 v[82:83], s[50:51], v82, s16, v[142:143]
	v_lshl_add_u64 v[82:83], v[82:83], 0, s[48:49]
	v_lshl_add_u64 v[82:83], v[82:83], 0, s[26:27]
	v_mul_f32_e32 v74, v176, v74
	v_mul_f32_e32 v75, v177, v75
	v_mul_f32_e32 v76, v178, v76
	v_mul_f32_e32 v77, v179, v77
	v_mul_f32_e32 v78, v180, v66
	v_mul_f32_e32 v79, v181, v67
	v_lshl_add_u64 v[70:71], v[82:83], 0, v[0:1]
	v_mul_f32_e32 v72, v182, v68
	v_mul_f32_e32 v69, v183, v69
	v_cvt_pk_bf16_f32 v66, v74, v75
	v_cvt_pk_bf16_f32 v67, v76, v77
	v_cvt_pk_bf16_f32 v68, v78, v79
	v_cvt_pk_bf16_f32 v69, v72, v69
	global_store_dwordx4 v[70:71], v[66:69], off
	s_nop 1
	v_mul_f32_e32 v176, 0xbfb8aa3b, v62
	v_mul_f32_e32 v177, 0xbfb8aa3b, v63
	v_mul_f32_e32 v178, 0xbfb8aa3b, v64
	v_mul_f32_e32 v179, 0xbfb8aa3b, v65
	v_mul_f32_e32 v180, 0xbfb8aa3b, v54
	v_mul_f32_e32 v181, 0xbfb8aa3b, v55
	v_mul_f32_e32 v182, 0xbfb8aa3b, v56
	v_mul_f32_e32 v183, 0xbfb8aa3b, v57
	v_exp_f32_e32 v176, v176
	v_exp_f32_e32 v177, v177
	v_exp_f32_e32 v178, v178
	v_exp_f32_e32 v179, v179
	v_exp_f32_e32 v180, v180
	v_exp_f32_e32 v181, v181
	v_exp_f32_e32 v182, v182
	v_exp_f32_e32 v183, v183
	v_add_f32_e32 v176, 1.0, v176
	v_add_f32_e32 v177, 1.0, v177
	v_add_f32_e32 v178, 1.0, v178
	v_add_f32_e32 v179, 1.0, v179
	v_add_f32_e32 v180, 1.0, v180
	v_add_f32_e32 v181, 1.0, v181
	v_add_f32_e32 v182, 1.0, v182
	v_add_f32_e32 v183, 1.0, v183
	v_rcp_f32_e32 v176, v176
	v_rcp_f32_e32 v177, v177
	v_rcp_f32_e32 v178, v178
	v_rcp_f32_e32 v179, v179
	v_rcp_f32_e32 v180, v180
	v_rcp_f32_e32 v181, v181
	v_rcp_f32_e32 v182, v182
	v_rcp_f32_e32 v183, v183
	v_mul_f32_e32 v176, v62, v176
	v_mul_f32_e32 v177, v63, v177
	v_mul_f32_e32 v178, v64, v178
	v_mul_f32_e32 v179, v65, v179
	v_mul_f32_e32 v180, v54, v180
	v_mul_f32_e32 v181, v55, v181
	v_mul_f32_e32 v182, v56, v182
	v_mul_f32_e32 v183, v57, v183
	v_add_u32_e32 v66, s6, v149
	v_mad_i64_i32 v[66:67], s[50:51], v66, s16, v[142:143]
	v_lshl_add_u64 v[66:67], v[66:67], 0, s[48:49]
	v_lshl_add_u64 v[66:67], v[66:67], 0, s[26:27]
	v_mul_f32_e32 v58, v176, v58
	v_mul_f32_e32 v59, v177, v59
	v_mul_f32_e32 v60, v178, v60
	v_mul_f32_e32 v61, v179, v61
	v_mul_f32_e32 v62, v180, v50
	v_mul_f32_e32 v63, v181, v51
	v_lshl_add_u64 v[54:55], v[66:67], 0, v[0:1]
	v_mul_f32_e32 v56, v182, v52
	v_mul_f32_e32 v53, v183, v53
	v_cvt_pk_bf16_f32 v50, v58, v59
	v_cvt_pk_bf16_f32 v51, v60, v61
	v_cvt_pk_bf16_f32 v52, v62, v63
	v_cvt_pk_bf16_f32 v53, v56, v53
	global_store_dwordx4 v[54:55], v[50:53], off
	s_nop 1
	v_mul_f32_e32 v176, 0xbfb8aa3b, v46
	v_mul_f32_e32 v177, 0xbfb8aa3b, v47
	v_mul_f32_e32 v178, 0xbfb8aa3b, v48
	v_mul_f32_e32 v179, 0xbfb8aa3b, v49
	v_mul_f32_e32 v180, 0xbfb8aa3b, v38
	v_mul_f32_e32 v181, 0xbfb8aa3b, v39
	v_mul_f32_e32 v182, 0xbfb8aa3b, v40
	v_mul_f32_e32 v183, 0xbfb8aa3b, v41
	v_exp_f32_e32 v176, v176
	v_exp_f32_e32 v177, v177
	v_exp_f32_e32 v178, v178
	v_exp_f32_e32 v179, v179
	v_exp_f32_e32 v180, v180
	v_exp_f32_e32 v181, v181
	v_exp_f32_e32 v182, v182
	v_exp_f32_e32 v183, v183
	v_add_f32_e32 v176, 1.0, v176
	v_add_f32_e32 v177, 1.0, v177
	v_add_f32_e32 v178, 1.0, v178
	v_add_f32_e32 v179, 1.0, v179
	v_add_f32_e32 v180, 1.0, v180
	v_add_f32_e32 v181, 1.0, v181
	v_add_f32_e32 v182, 1.0, v182
	v_add_f32_e32 v183, 1.0, v183
	v_rcp_f32_e32 v176, v176
	v_rcp_f32_e32 v177, v177
	v_rcp_f32_e32 v178, v178
	v_rcp_f32_e32 v179, v179
	v_rcp_f32_e32 v180, v180
	v_rcp_f32_e32 v181, v181
	v_rcp_f32_e32 v182, v182
	v_rcp_f32_e32 v183, v183
	v_mul_f32_e32 v176, v46, v176
	v_mul_f32_e32 v177, v47, v177
	v_mul_f32_e32 v178, v48, v178
	v_mul_f32_e32 v179, v49, v179
	v_mul_f32_e32 v180, v38, v180
	v_mul_f32_e32 v181, v39, v181
	v_mul_f32_e32 v182, v40, v182
	v_mul_f32_e32 v183, v41, v183
	v_add_u32_e32 v50, s6, v150
	v_mad_i64_i32 v[50:51], s[50:51], v50, s16, v[142:143]
	v_lshl_add_u64 v[50:51], v[50:51], 0, s[48:49]
	v_lshl_add_u64 v[50:51], v[50:51], 0, s[26:27]
	v_mul_f32_e32 v42, v176, v42
	v_mul_f32_e32 v43, v177, v43
	v_mul_f32_e32 v44, v178, v44
	v_mul_f32_e32 v45, v179, v45
	v_mul_f32_e32 v46, v180, v34
	v_mul_f32_e32 v47, v181, v35
	v_lshl_add_u64 v[38:39], v[50:51], 0, v[0:1]
	v_mul_f32_e32 v40, v182, v36
	v_mul_f32_e32 v37, v183, v37
	v_cvt_pk_bf16_f32 v34, v42, v43
	v_cvt_pk_bf16_f32 v35, v44, v45
	v_cvt_pk_bf16_f32 v36, v46, v47
	v_cvt_pk_bf16_f32 v37, v40, v37
	global_store_dwordx4 v[38:39], v[34:37], off
	s_nop 1
	v_mul_f32_e32 v176, 0xbfb8aa3b, v30
	v_mul_f32_e32 v177, 0xbfb8aa3b, v31
	v_mul_f32_e32 v178, 0xbfb8aa3b, v32
	v_mul_f32_e32 v179, 0xbfb8aa3b, v33
	v_mul_f32_e32 v180, 0xbfb8aa3b, v22
	v_mul_f32_e32 v181, 0xbfb8aa3b, v23
	v_mul_f32_e32 v182, 0xbfb8aa3b, v24
	v_mul_f32_e32 v183, 0xbfb8aa3b, v25
	v_exp_f32_e32 v176, v176
	v_exp_f32_e32 v177, v177
	v_exp_f32_e32 v178, v178
	v_exp_f32_e32 v179, v179
	v_exp_f32_e32 v180, v180
	v_exp_f32_e32 v181, v181
	v_exp_f32_e32 v182, v182
	v_exp_f32_e32 v183, v183
	v_add_f32_e32 v176, 1.0, v176
	v_add_f32_e32 v177, 1.0, v177
	v_add_f32_e32 v178, 1.0, v178
	v_add_f32_e32 v179, 1.0, v179
	v_add_f32_e32 v180, 1.0, v180
	v_add_f32_e32 v181, 1.0, v181
	v_add_f32_e32 v182, 1.0, v182
	v_add_f32_e32 v183, 1.0, v183
	v_rcp_f32_e32 v176, v176
	v_rcp_f32_e32 v177, v177
	v_rcp_f32_e32 v178, v178
	v_rcp_f32_e32 v179, v179
	v_rcp_f32_e32 v180, v180
	v_rcp_f32_e32 v181, v181
	v_rcp_f32_e32 v182, v182
	v_rcp_f32_e32 v183, v183
	v_mul_f32_e32 v176, v30, v176
	v_mul_f32_e32 v177, v31, v177
	v_mul_f32_e32 v178, v32, v178
	v_mul_f32_e32 v179, v33, v179
	v_mul_f32_e32 v180, v22, v180
	v_mul_f32_e32 v181, v23, v181
	v_mul_f32_e32 v182, v24, v182
	v_mul_f32_e32 v183, v25, v183
	v_add_u32_e32 v34, s6, v151
	v_mad_i64_i32 v[34:35], s[50:51], v34, s16, v[142:143]
	v_lshl_add_u64 v[34:35], v[34:35], 0, s[48:49]
	v_lshl_add_u64 v[34:35], v[34:35], 0, s[26:27]
	v_mul_f32_e32 v26, v176, v26
	v_mul_f32_e32 v27, v177, v27
	v_mul_f32_e32 v28, v178, v28
	v_mul_f32_e32 v29, v179, v29
	v_mul_f32_e32 v30, v180, v18
	v_mul_f32_e32 v31, v181, v19
	v_lshl_add_u64 v[22:23], v[34:35], 0, v[0:1]
	v_mul_f32_e32 v24, v182, v20
	v_mul_f32_e32 v21, v183, v21
	v_cvt_pk_bf16_f32 v18, v26, v27
	v_cvt_pk_bf16_f32 v19, v28, v29
	v_cvt_pk_bf16_f32 v20, v30, v31
	v_cvt_pk_bf16_f32 v21, v24, v21
	global_store_dwordx4 v[22:23], v[18:21], off
	s_nop 1
	v_mul_f32_e32 v176, 0xbfb8aa3b, v14
	v_mul_f32_e32 v177, 0xbfb8aa3b, v15
	v_mul_f32_e32 v178, 0xbfb8aa3b, v16
	v_mul_f32_e32 v179, 0xbfb8aa3b, v17
	v_mul_f32_e32 v180, 0xbfb8aa3b, v6
	v_mul_f32_e32 v181, 0xbfb8aa3b, v7
	v_mul_f32_e32 v182, 0xbfb8aa3b, v8
	v_mul_f32_e32 v183, 0xbfb8aa3b, v9
	v_exp_f32_e32 v176, v176
	v_exp_f32_e32 v177, v177
	v_exp_f32_e32 v178, v178
	v_exp_f32_e32 v179, v179
	v_exp_f32_e32 v180, v180
	v_exp_f32_e32 v181, v181
	v_exp_f32_e32 v182, v182
	v_exp_f32_e32 v183, v183
	v_add_f32_e32 v176, 1.0, v176
	v_add_f32_e32 v177, 1.0, v177
	v_add_f32_e32 v178, 1.0, v178
	v_add_f32_e32 v179, 1.0, v179
	v_add_f32_e32 v180, 1.0, v180
	v_add_f32_e32 v181, 1.0, v181
	v_add_f32_e32 v182, 1.0, v182
	v_add_f32_e32 v183, 1.0, v183
	v_rcp_f32_e32 v176, v176
	v_rcp_f32_e32 v177, v177
	v_rcp_f32_e32 v178, v178
	v_rcp_f32_e32 v179, v179
	v_rcp_f32_e32 v180, v180
	v_rcp_f32_e32 v181, v181
	v_rcp_f32_e32 v182, v182
	v_rcp_f32_e32 v183, v183
	v_mul_f32_e32 v176, v14, v176
	v_mul_f32_e32 v177, v15, v177
	v_mul_f32_e32 v178, v16, v178
	v_mul_f32_e32 v179, v17, v179
	v_mul_f32_e32 v180, v6, v180
	v_mul_f32_e32 v181, v7, v181
	v_mul_f32_e32 v182, v8, v182
	v_mul_f32_e32 v183, v9, v183
	v_add_u32_e32 v18, s6, v152
	v_mad_i64_i32 v[18:19], s[50:51], v18, s16, v[142:143]
	v_lshl_add_u64 v[18:19], v[18:19], 0, s[48:49]
	v_lshl_add_u64 v[18:19], v[18:19], 0, s[26:27]
	s_mov_b64 s[48:49], -1
	v_mul_f32_e32 v10, v176, v10
	v_mul_f32_e32 v11, v177, v11
	v_mul_f32_e32 v12, v178, v12
	v_mul_f32_e32 v13, v179, v13
	v_mul_f32_e32 v14, v180, v2
	v_mul_f32_e32 v15, v181, v3
	v_lshl_add_u64 v[6:7], v[18:19], 0, v[0:1]
	v_mul_f32_e32 v8, v182, v4
	v_mul_f32_e32 v5, v183, v5
	v_cvt_pk_bf16_f32 v2, v10, v11
	v_cvt_pk_bf16_f32 v3, v12, v13
	v_cvt_pk_bf16_f32 v4, v14, v15
	v_cvt_pk_bf16_f32 v5, v8, v5
	global_store_dwordx4 v[6:7], v[2:5], off
	s_cbranch_vccnz .LBB0_428
	s_andn2_b64 vcc, exec, s[0:1]
	s_cbranch_vccnz .LBB0_427
	s_barrier
	s_branch .LBB0_427
